# v15 + first-iteration vmcnt relax (stores drain under K-tile 0) also in P8 and both P4 instances
# speedup vs baseline: 1.0052x; 1.0052x over previous
.LBB0_1008:
	s_add_u32 s20, s18, 0xfffc0080
	s_addc_u32 s21, s19, -1
	s_add_i32 s49, 0, 0x10000
	s_cmp_eq_u32 s48, 12
	s_cselect_b32 s23, s13, s21
	s_cselect_b32 s22, s44, s20
	s_cselect_b32 s21, s11, s47
	s_cselect_b32 s20, s45, s46
	s_add_i32 s52, 0, 0x14000
	v_add_u32_e32 v148, s49, v166
	v_add_u32_e32 v164, s52, v166
	ds_read_b128 v[136:139], v148
	ds_read_b128 v[140:143], v148 offset:1024
	ds_read_b128 v[144:147], v148 offset:2048
	ds_read_b128 v[148:151], v148 offset:3072
	ds_read_b128 v[152:155], v164
	ds_read_b128 v[156:159], v164 offset:1024
	ds_read_b128 v[160:163], v164 offset:2048
	ds_read_b128 v[168:171], v164 offset:3072
	v_lshl_add_u64 v[164:165], s[18:19], 0, v[132:133]
	s_add_i32 m0, s29, 0xc000
	ds_read_b128 v[172:175], v167
	ds_read_b128 v[176:179], v167 offset:1024
	ds_read_b128 v[180:183], v167 offset:2048
	ds_read_b128 v[184:187], v167 offset:3072
	ds_read_b128 v[188:191], v167 offset:4096
	ds_read_b128 v[192:195], v167 offset:5120
	ds_read_b128 v[202:205], v167 offset:6144
	ds_read_b128 v[214:217], v167 offset:7168
	global_load_lds_dwordx4 v[164:165], off
	v_lshl_add_u64 v[164:165], s[18:19], 0, v[134:135]
	s_add_i32 m0, s29, 0xe000
	s_nop 0
	global_load_lds_dwordx4 v[164:165], off
	s_cmp_eq_u32 s48, -2
	s_cbranch_scc1 .Lp8_f0
	s_waitcnt vmcnt(8)
	s_branch .Lp8_j0
.Lp8_f0:
	s_waitcnt vmcnt(63)
.Lp8_j0:
	s_waitcnt lgkmcnt(0)
	s_barrier
	s_setprio 1
	s_waitcnt lgkmcnt(0)
	v_mfma_f32_16x16x32_bf16 v[126:129], v[136:139], v[172:175], v[126:129]
	v_mfma_f32_16x16x32_bf16 v[122:125], v[144:147], v[172:175], v[122:125]
	v_mfma_f32_16x16x32_bf16 v[114:117], v[136:139], v[180:183], v[114:117]
	v_mfma_f32_16x16x32_bf16 v[106:109], v[144:147], v[180:183], v[106:109]
	v_mfma_f32_16x16x32_bf16 v[98:101], v[136:139], v[188:191], v[98:101]
	v_mfma_f32_16x16x32_bf16 v[90:93], v[144:147], v[188:191], v[90:93]
	v_mfma_f32_16x16x32_bf16 v[82:85], v[136:139], v[202:205], v[82:85]
	v_mfma_f32_16x16x32_bf16 v[74:77], v[144:147], v[202:205], v[74:77]
	v_mfma_f32_16x16x32_bf16 v[126:129], v[140:143], v[176:179], v[126:129]
	v_mfma_f32_16x16x32_bf16 v[122:125], v[148:151], v[176:179], v[122:125]
	v_mfma_f32_16x16x32_bf16 v[114:117], v[140:143], v[184:187], v[114:117]
	v_mfma_f32_16x16x32_bf16 v[106:109], v[148:151], v[184:187], v[106:109]
	v_mfma_f32_16x16x32_bf16 v[98:101], v[140:143], v[192:195], v[98:101]
	v_mfma_f32_16x16x32_bf16 v[90:93], v[148:151], v[192:195], v[90:93]
	v_mfma_f32_16x16x32_bf16 v[82:85], v[140:143], v[214:217], v[82:85]
	v_mfma_f32_16x16x32_bf16 v[74:77], v[148:151], v[214:217], v[74:77]
	s_setprio 0
	s_setprio 1
	v_mfma_f32_16x16x32_bf16 v[118:121], v[152:155], v[172:175], v[118:121]
	v_mfma_f32_16x16x32_bf16 v[110:113], v[160:163], v[172:175], v[110:113]
	v_mfma_f32_16x16x32_bf16 v[102:105], v[152:155], v[180:183], v[102:105]
	v_mfma_f32_16x16x32_bf16 v[94:97], v[160:163], v[180:183], v[94:97]
	v_mfma_f32_16x16x32_bf16 v[86:89], v[152:155], v[188:191], v[86:89]
	v_mfma_f32_16x16x32_bf16 v[78:81], v[160:163], v[188:191], v[78:81]
	v_mfma_f32_16x16x32_bf16 v[70:73], v[152:155], v[202:205], v[70:73]
	v_mfma_f32_16x16x32_bf16 v[66:69], v[160:163], v[202:205], v[66:69]
	v_mfma_f32_16x16x32_bf16 v[118:121], v[156:159], v[176:179], v[118:121]
	v_mfma_f32_16x16x32_bf16 v[110:113], v[168:171], v[176:179], v[110:113]
	v_mfma_f32_16x16x32_bf16 v[102:105], v[156:159], v[184:187], v[102:105]
	v_mfma_f32_16x16x32_bf16 v[94:97], v[168:171], v[184:187], v[94:97]
	v_mfma_f32_16x16x32_bf16 v[86:89], v[156:159], v[192:195], v[86:89]
	v_mfma_f32_16x16x32_bf16 v[78:81], v[168:171], v[192:195], v[78:81]
	v_mfma_f32_16x16x32_bf16 v[70:73], v[156:159], v[214:217], v[70:73]
	v_mfma_f32_16x16x32_bf16 v[66:69], v[168:171], v[214:217], v[66:69]
	s_setprio 0
	s_barrier
	s_add_i32 s49, s49, s28
	v_lshl_add_u64 v[164:165], s[20:21], 0, v[0:1]
	s_mov_b32 m0, s49
	ds_read_b128 v[172:175], v167 offset:16384
	ds_read_b128 v[176:179], v167 offset:17408
	ds_read_b128 v[180:183], v167 offset:18432
	ds_read_b128 v[184:187], v167 offset:19456
	ds_read_b128 v[188:191], v167 offset:20480
	ds_read_b128 v[192:195], v167 offset:21504
	ds_read_b128 v[202:205], v167 offset:22528
	ds_read_b128 v[214:217], v167 offset:23552
	global_load_lds_dwordx4 v[164:165], off
	s_add_i32 m0, s49, 0x2000
	s_add_u32 s50, s20, 0x40000
	v_lshl_add_u64 v[196:197], s[20:21], 0, v[130:131]
	s_addc_u32 s51, s21, 0
	s_add_i32 s49, s52, s28
	global_load_lds_dwordx4 v[196:197], off
	v_lshl_add_u64 v[198:199], s[50:51], 0, v[0:1]
	s_mov_b32 m0, s49
	v_lshl_add_u64 v[200:201], s[22:23], 0, v[130:131]
	global_load_lds_dwordx4 v[198:199], off
	v_lshl_add_u64 v[198:199], s[50:51], 0, v[130:131]
	s_add_i32 m0, s49, 0x2000
	s_nop 0
	global_load_lds_dwordx4 v[198:199], off
	v_lshl_add_u64 v[198:199], s[22:23], 0, v[0:1]
	s_mov_b32 m0, s29
	s_nop 0
	global_load_lds_dwordx4 v[198:199], off
	s_mov_b32 m0, s30
	s_nop 0
	global_load_lds_dwordx4 v[200:201], off
	s_cmp_eq_u32 s48, -2
	s_cbranch_scc1 .Lp8_f1
	s_waitcnt vmcnt(8)
	s_branch .Lp8_j1

.Lp8_j1:
	s_waitcnt lgkmcnt(0)
	s_barrier
	s_setprio 1
	s_waitcnt lgkmcnt(0)
	v_mfma_f32_16x16x32_bf16 v[62:65], v[136:139], v[172:175], v[62:65]
	v_mfma_f32_16x16x32_bf16 v[58:61], v[144:147], v[172:175], v[58:61]
	v_mfma_f32_16x16x32_bf16 v[50:53], v[136:139], v[180:183], v[50:53]
	v_mfma_f32_16x16x32_bf16 v[42:45], v[144:147], v[180:183], v[42:45]
	v_mfma_f32_16x16x32_bf16 v[34:37], v[136:139], v[188:191], v[34:37]
	v_mfma_f32_16x16x32_bf16 v[26:29], v[144:147], v[188:191], v[26:29]
	v_mfma_f32_16x16x32_bf16 v[18:21], v[136:139], v[202:205], v[18:21]
	v_mfma_f32_16x16x32_bf16 v[10:13], v[144:147], v[202:205], v[10:13]
	v_mfma_f32_16x16x32_bf16 v[62:65], v[140:143], v[176:179], v[62:65]
	v_mfma_f32_16x16x32_bf16 v[58:61], v[148:151], v[176:179], v[58:61]
	v_mfma_f32_16x16x32_bf16 v[50:53], v[140:143], v[184:187], v[50:53]
	v_mfma_f32_16x16x32_bf16 v[42:45], v[148:151], v[184:187], v[42:45]
	v_mfma_f32_16x16x32_bf16 v[34:37], v[140:143], v[192:195], v[34:37]
	v_mfma_f32_16x16x32_bf16 v[26:29], v[148:151], v[192:195], v[26:29]
	v_mfma_f32_16x16x32_bf16 v[18:21], v[140:143], v[214:217], v[18:21]
	v_mfma_f32_16x16x32_bf16 v[10:13], v[148:151], v[214:217], v[10:13]
	s_setprio 0
	s_setprio 1
	v_mfma_f32_16x16x32_bf16 v[54:57], v[152:155], v[172:175], v[54:57]
	v_mfma_f32_16x16x32_bf16 v[46:49], v[160:163], v[172:175], v[46:49]
	v_mfma_f32_16x16x32_bf16 v[38:41], v[152:155], v[180:183], v[38:41]
	v_mfma_f32_16x16x32_bf16 v[30:33], v[160:163], v[180:183], v[30:33]
	v_mfma_f32_16x16x32_bf16 v[22:25], v[152:155], v[188:191], v[22:25]
	v_mfma_f32_16x16x32_bf16 v[14:17], v[160:163], v[188:191], v[14:17]
	v_mfma_f32_16x16x32_bf16 v[6:9], v[152:155], v[202:205], v[6:9]
	v_mfma_f32_16x16x32_bf16 v[2:5], v[160:163], v[202:205], v[2:5]
	v_mfma_f32_16x16x32_bf16 v[54:57], v[156:159], v[176:179], v[54:57]
	v_mfma_f32_16x16x32_bf16 v[46:49], v[168:171], v[176:179], v[46:49]
	v_mfma_f32_16x16x32_bf16 v[38:41], v[156:159], v[184:187], v[38:41]
	v_mfma_f32_16x16x32_bf16 v[30:33], v[168:171], v[184:187], v[30:33]
	v_mfma_f32_16x16x32_bf16 v[22:25], v[156:159], v[192:195], v[22:25]
	v_mfma_f32_16x16x32_bf16 v[14:17], v[168:171], v[192:195], v[14:17]
	v_mfma_f32_16x16x32_bf16 v[6:9], v[156:159], v[214:217], v[6:9]
	v_mfma_f32_16x16x32_bf16 v[2:5], v[168:171], v[214:217], v[2:5]
	s_setprio 0
	s_barrier
	s_add_i32 s49, 0, 0x18000
	s_add_i32 s50, 0, 0x1c000
	v_add_u32_e32 v148, s49, v166
	v_add_u32_e32 v168, s50, v166
	ds_read_b128 v[136:139], v148
	ds_read_b128 v[140:143], v148 offset:1024
	ds_read_b128 v[144:147], v148 offset:2048
	ds_read_b128 v[148:151], v148 offset:3072
	ds_read_b128 v[152:155], v168
	ds_read_b128 v[156:159], v168 offset:1024
	ds_read_b128 v[160:163], v168 offset:2048
	ds_read_b128 v[168:171], v168 offset:3072
	s_add_u32 s22, s22, 0x40000
	s_addc_u32 s23, s23, 0
	s_mov_b32 m0, s31
	v_lshl_add_u64 v[206:207], s[22:23], 0, v[0:1]
	ds_read_b128 v[172:175], v167 offset:32768
	ds_read_b128 v[176:179], v167 offset:33792
	ds_read_b128 v[180:183], v167 offset:34816
	ds_read_b128 v[184:187], v167 offset:35840
	ds_read_b128 v[188:191], v167 offset:36864
	ds_read_b128 v[192:195], v167 offset:37888
	ds_read_b128 v[202:205], v167 offset:38912
	ds_read_b128 v[214:217], v167 offset:39936
	global_load_lds_dwordx4 v[206:207], off
	v_lshl_add_u64 v[206:207], s[22:23], 0, v[130:131]
	s_mov_b32 m0, s34
	s_nop 0
	global_load_lds_dwordx4 v[206:207], off
	s_waitcnt vmcnt(8)
	s_waitcnt lgkmcnt(0)
	s_barrier
	s_setprio 1
	s_waitcnt lgkmcnt(0)
	v_mfma_f32_16x16x32_bf16 v[126:129], v[136:139], v[172:175], v[126:129]
	v_mfma_f32_16x16x32_bf16 v[122:125], v[144:147], v[172:175], v[122:125]
	v_mfma_f32_16x16x32_bf16 v[114:117], v[136:139], v[180:183], v[114:117]
	v_mfma_f32_16x16x32_bf16 v[106:109], v[144:147], v[180:183], v[106:109]
	v_mfma_f32_16x16x32_bf16 v[98:101], v[136:139], v[188:191], v[98:101]
	v_mfma_f32_16x16x32_bf16 v[90:93], v[144:147], v[188:191], v[90:93]
	v_mfma_f32_16x16x32_bf16 v[82:85], v[136:139], v[202:205], v[82:85]
	v_mfma_f32_16x16x32_bf16 v[74:77], v[144:147], v[202:205], v[74:77]
	v_mfma_f32_16x16x32_bf16 v[126:129], v[140:143], v[176:179], v[126:129]
	v_mfma_f32_16x16x32_bf16 v[122:125], v[148:151], v[176:179], v[122:125]
	v_mfma_f32_16x16x32_bf16 v[114:117], v[140:143], v[184:187], v[114:117]
	v_mfma_f32_16x16x32_bf16 v[106:109], v[148:151], v[184:187], v[106:109]
	v_mfma_f32_16x16x32_bf16 v[98:101], v[140:143], v[192:195], v[98:101]
	v_mfma_f32_16x16x32_bf16 v[90:93], v[148:151], v[192:195], v[90:93]
	v_mfma_f32_16x16x32_bf16 v[82:85], v[140:143], v[214:217], v[82:85]
	v_mfma_f32_16x16x32_bf16 v[74:77], v[148:151], v[214:217], v[74:77]
	s_setprio 0
	s_setprio 1
	v_mfma_f32_16x16x32_bf16 v[118:121], v[152:155], v[172:175], v[118:121]
	v_mfma_f32_16x16x32_bf16 v[110:113], v[160:163], v[172:175], v[110:113]
	v_mfma_f32_16x16x32_bf16 v[102:105], v[152:155], v[180:183], v[102:105]
	v_mfma_f32_16x16x32_bf16 v[94:97], v[160:163], v[180:183], v[94:97]
	v_mfma_f32_16x16x32_bf16 v[86:89], v[152:155], v[188:191], v[86:89]
	v_mfma_f32_16x16x32_bf16 v[78:81], v[160:163], v[188:191], v[78:81]
	v_mfma_f32_16x16x32_bf16 v[70:73], v[152:155], v[202:205], v[70:73]
	v_mfma_f32_16x16x32_bf16 v[66:69], v[160:163], v[202:205], v[66:69]
	v_mfma_f32_16x16x32_bf16 v[118:121], v[156:159], v[176:179], v[118:121]
	v_mfma_f32_16x16x32_bf16 v[110:113], v[168:171], v[176:179], v[110:113]
	v_mfma_f32_16x16x32_bf16 v[102:105], v[156:159], v[184:187], v[102:105]
	v_mfma_f32_16x16x32_bf16 v[94:97], v[168:171], v[184:187], v[94:97]
	v_mfma_f32_16x16x32_bf16 v[86:89], v[156:159], v[192:195], v[86:89]
	v_mfma_f32_16x16x32_bf16 v[78:81], v[168:171], v[192:195], v[78:81]
	v_mfma_f32_16x16x32_bf16 v[70:73], v[156:159], v[214:217], v[70:73]
	v_mfma_f32_16x16x32_bf16 v[66:69], v[168:171], v[214:217], v[66:69]
	s_setprio 0
	s_barrier
	s_add_i32 s22, s49, s28
	v_lshl_add_u64 v[164:165], v[164:165], 0, s[94:95]
	s_mov_b32 m0, s22
	ds_read_b128 v[172:175], v167 offset:49152
	ds_read_b128 v[176:179], v167 offset:50176
	ds_read_b128 v[180:183], v167 offset:51200
	ds_read_b128 v[184:187], v167 offset:52224
	ds_read_b128 v[188:191], v167 offset:53248
	ds_read_b128 v[192:195], v167 offset:54272
	ds_read_b128 v[202:205], v167 offset:55296
	ds_read_b128 v[214:217], v167 offset:56320
	global_load_lds_dwordx4 v[164:165], off
	s_add_i32 m0, s22, 0x2000
	s_add_u32 s20, s20, 0x40080
	v_lshl_add_u64 v[164:165], v[196:197], 0, s[94:95]
	s_addc_u32 s21, s21, 0
	s_add_i32 s22, s50, s28
	global_load_lds_dwordx4 v[164:165], off
	v_lshl_add_u64 v[164:165], s[20:21], 0, v[0:1]
	s_mov_b32 m0, s22
	s_nop 0
	global_load_lds_dwordx4 v[164:165], off
	v_lshl_add_u64 v[164:165], s[20:21], 0, v[130:131]
	s_add_i32 m0, s22, 0x2000
	s_nop 0
	global_load_lds_dwordx4 v[164:165], off
	v_lshl_add_u64 v[164:165], v[198:199], 0, s[94:95]
	s_mov_b32 m0, s37
	s_nop 0
	global_load_lds_dwordx4 v[164:165], off
	v_lshl_add_u64 v[164:165], v[200:201], 0, s[94:95]
	s_mov_b32 m0, s38
	s_nop 0
	global_load_lds_dwordx4 v[164:165], off
	s_waitcnt vmcnt(8)
	s_waitcnt lgkmcnt(0)
	s_barrier
	s_setprio 1
	s_waitcnt lgkmcnt(0)
	v_mfma_f32_16x16x32_bf16 v[62:65], v[136:139], v[172:175], v[62:65]
	v_mfma_f32_16x16x32_bf16 v[58:61], v[144:147], v[172:175], v[58:61]
	v_mfma_f32_16x16x32_bf16 v[50:53], v[136:139], v[180:183], v[50:53]
	v_mfma_f32_16x16x32_bf16 v[42:45], v[144:147], v[180:183], v[42:45]
	v_mfma_f32_16x16x32_bf16 v[34:37], v[136:139], v[188:191], v[34:37]
	v_mfma_f32_16x16x32_bf16 v[26:29], v[144:147], v[188:191], v[26:29]
	v_mfma_f32_16x16x32_bf16 v[18:21], v[136:139], v[202:205], v[18:21]
	v_mfma_f32_16x16x32_bf16 v[10:13], v[144:147], v[202:205], v[10:13]
	v_mfma_f32_16x16x32_bf16 v[62:65], v[140:143], v[176:179], v[62:65]
	v_mfma_f32_16x16x32_bf16 v[58:61], v[148:151], v[176:179], v[58:61]
	v_mfma_f32_16x16x32_bf16 v[50:53], v[140:143], v[184:187], v[50:53]
	v_mfma_f32_16x16x32_bf16 v[42:45], v[148:151], v[184:187], v[42:45]
	v_mfma_f32_16x16x32_bf16 v[34:37], v[140:143], v[192:195], v[34:37]
	v_mfma_f32_16x16x32_bf16 v[26:29], v[148:151], v[192:195], v[26:29]
	v_mfma_f32_16x16x32_bf16 v[18:21], v[140:143], v[214:217], v[18:21]
	v_mfma_f32_16x16x32_bf16 v[10:13], v[148:151], v[214:217], v[10:13]
	s_setprio 0
	s_setprio 1
	v_mfma_f32_16x16x32_bf16 v[54:57], v[152:155], v[172:175], v[54:57]
	v_mfma_f32_16x16x32_bf16 v[46:49], v[160:163], v[172:175], v[46:49]
	v_mfma_f32_16x16x32_bf16 v[38:41], v[152:155], v[180:183], v[38:41]
	v_mfma_f32_16x16x32_bf16 v[30:33], v[160:163], v[180:183], v[30:33]
	v_mfma_f32_16x16x32_bf16 v[22:25], v[152:155], v[188:191], v[22:25]
	v_mfma_f32_16x16x32_bf16 v[14:17], v[160:163], v[188:191], v[14:17]
	v_mfma_f32_16x16x32_bf16 v[6:9], v[152:155], v[202:205], v[6:9]
	v_mfma_f32_16x16x32_bf16 v[2:5], v[160:163], v[202:205], v[2:5]
	v_mfma_f32_16x16x32_bf16 v[54:57], v[156:159], v[176:179], v[54:57]
	v_mfma_f32_16x16x32_bf16 v[46:49], v[168:171], v[176:179], v[46:49]
	v_mfma_f32_16x16x32_bf16 v[38:41], v[156:159], v[184:187], v[38:41]
	v_mfma_f32_16x16x32_bf16 v[30:33], v[168:171], v[184:187], v[30:33]
	v_mfma_f32_16x16x32_bf16 v[22:25], v[156:159], v[192:195], v[22:25]
	v_mfma_f32_16x16x32_bf16 v[14:17], v[168:171], v[192:195], v[14:17]
	v_mfma_f32_16x16x32_bf16 v[6:9], v[156:159], v[214:217], v[6:9]
	v_mfma_f32_16x16x32_bf16 v[2:5], v[168:171], v[214:217], v[2:5]
	s_setprio 0
	s_barrier
	s_add_i32 s48, s48, 2
	s_add_u32 s18, s18, 0x100
	s_addc_u32 s19, s19, 0
	s_add_u32 s46, s46, 0x100
	s_addc_u32 s47, s47, 0
	s_cmp_gt_u32 s48, 13
	s_cbranch_scc0 .LBB0_1008
	s_and_b64 vcc, exec, s[8:9]
	s_cbranch_vccz .LBB0_1011
	s_barrier

.LBB0_1316:
	s_add_u32 s20, s18, 0x100
	s_addc_u32 s21, s19, 0
	s_add_i32 s51, 0, 0x10000
	s_cmp_eq_u32 s50, 40
	s_cselect_b32 s25, s11, s21
	s_cselect_b32 s24, s10, s20
	s_cselect_b32 s23, s17, s49
	s_cselect_b32 s22, s16, s48
	s_add_i32 s52, 0, 0x14000
	v_add_u32_e32 v150, s51, v144
	v_add_u32_e32 v166, s52, v144
	ds_read_b128 v[136:139], v150
	ds_read_b128 v[140:143], v150 offset:1024
	ds_read_b128 v[146:149], v150 offset:2048
	ds_read_b128 v[150:153], v150 offset:3072
	ds_read_b128 v[154:157], v166
	ds_read_b128 v[158:161], v166 offset:1024
	ds_read_b128 v[162:165], v166 offset:2048
	ds_read_b128 v[166:169], v166 offset:3072
	v_lshl_add_u64 v[202:203], s[18:19], 0, v[132:133]
	s_add_i32 m0, s31, 0xc000
	ds_read_b128 v[170:173], v145
	ds_read_b128 v[174:177], v145 offset:1024
	ds_read_b128 v[178:181], v145 offset:2048
	ds_read_b128 v[182:185], v145 offset:3072
	ds_read_b128 v[186:189], v145 offset:4096
	ds_read_b128 v[190:193], v145 offset:5120
	ds_read_b128 v[194:197], v145 offset:6144
	ds_read_b128 v[198:201], v145 offset:7168
	global_load_lds_dwordx4 v[202:203], off
	v_lshl_add_u64 v[202:203], s[18:19], 0, v[134:135]
	s_add_i32 m0, s31, 0xe000
	s_nop 0
	global_load_lds_dwordx4 v[202:203], off
	s_cmp_eq_u32 s50, -2
	s_cbranch_scc1 .Lp4b_f0
	s_waitcnt vmcnt(8)
	s_branch .Lp4b_j0

.Lp4b_j0:
	s_waitcnt lgkmcnt(0)
	s_barrier
	s_setprio 1
	s_waitcnt lgkmcnt(0)
	v_mfma_f32_16x16x32_bf16 v[126:129], v[136:139], v[170:173], v[126:129]
	v_mfma_f32_16x16x32_bf16 v[122:125], v[146:149], v[170:173], v[122:125]
	v_mfma_f32_16x16x32_bf16 v[114:117], v[136:139], v[178:181], v[114:117]
	v_mfma_f32_16x16x32_bf16 v[106:109], v[146:149], v[178:181], v[106:109]
	v_mfma_f32_16x16x32_bf16 v[98:101], v[136:139], v[186:189], v[98:101]
	v_mfma_f32_16x16x32_bf16 v[90:93], v[146:149], v[186:189], v[90:93]
	v_mfma_f32_16x16x32_bf16 v[82:85], v[136:139], v[194:197], v[82:85]
	v_mfma_f32_16x16x32_bf16 v[74:77], v[146:149], v[194:197], v[74:77]
	v_mfma_f32_16x16x32_bf16 v[126:129], v[140:143], v[174:177], v[126:129]
	v_mfma_f32_16x16x32_bf16 v[122:125], v[150:153], v[174:177], v[122:125]
	v_mfma_f32_16x16x32_bf16 v[114:117], v[140:143], v[182:185], v[114:117]
	v_mfma_f32_16x16x32_bf16 v[106:109], v[150:153], v[182:185], v[106:109]
	v_mfma_f32_16x16x32_bf16 v[98:101], v[140:143], v[190:193], v[98:101]
	v_mfma_f32_16x16x32_bf16 v[90:93], v[150:153], v[190:193], v[90:93]
	v_mfma_f32_16x16x32_bf16 v[82:85], v[140:143], v[198:201], v[82:85]
	v_mfma_f32_16x16x32_bf16 v[74:77], v[150:153], v[198:201], v[74:77]
	s_setprio 0
	s_setprio 1
	v_mfma_f32_16x16x32_bf16 v[118:121], v[154:157], v[170:173], v[118:121]
	v_mfma_f32_16x16x32_bf16 v[110:113], v[162:165], v[170:173], v[110:113]
	v_mfma_f32_16x16x32_bf16 v[102:105], v[154:157], v[178:181], v[102:105]
	v_mfma_f32_16x16x32_bf16 v[94:97], v[162:165], v[178:181], v[94:97]
	v_mfma_f32_16x16x32_bf16 v[86:89], v[154:157], v[186:189], v[86:89]
	v_mfma_f32_16x16x32_bf16 v[78:81], v[162:165], v[186:189], v[78:81]
	v_mfma_f32_16x16x32_bf16 v[70:73], v[154:157], v[194:197], v[70:73]
	v_mfma_f32_16x16x32_bf16 v[66:69], v[162:165], v[194:197], v[66:69]
	v_mfma_f32_16x16x32_bf16 v[118:121], v[158:161], v[174:177], v[118:121]
	v_mfma_f32_16x16x32_bf16 v[110:113], v[166:169], v[174:177], v[110:113]
	v_mfma_f32_16x16x32_bf16 v[102:105], v[158:161], v[182:185], v[102:105]
	v_mfma_f32_16x16x32_bf16 v[94:97], v[166:169], v[182:185], v[94:97]
	v_mfma_f32_16x16x32_bf16 v[86:89], v[158:161], v[190:193], v[86:89]
	v_mfma_f32_16x16x32_bf16 v[78:81], v[166:169], v[190:193], v[78:81]
	v_mfma_f32_16x16x32_bf16 v[70:73], v[158:161], v[198:201], v[70:73]
	v_mfma_f32_16x16x32_bf16 v[66:69], v[166:169], v[198:201], v[66:69]
	s_setprio 0
	s_barrier
	s_add_i32 s18, s51, s30
	v_lshl_add_u64 v[202:203], s[22:23], 0, v[0:1]
	s_mov_b32 m0, s18
	ds_read_b128 v[170:173], v145 offset:16384
	ds_read_b128 v[174:177], v145 offset:17408
	ds_read_b128 v[178:181], v145 offset:18432
	ds_read_b128 v[182:185], v145 offset:19456
	ds_read_b128 v[186:189], v145 offset:20480
	ds_read_b128 v[190:193], v145 offset:21504
	ds_read_b128 v[194:197], v145 offset:22528
	ds_read_b128 v[198:201], v145 offset:23552
	global_load_lds_dwordx4 v[202:203], off
	s_add_i32 m0, s18, 0x2000
	s_add_u32 s18, s22, 0xb0000
	v_lshl_add_u64 v[204:205], s[22:23], 0, v[130:131]
	s_addc_u32 s19, s23, 0
	s_add_i32 s51, s52, s30
	global_load_lds_dwordx4 v[204:205], off
	v_lshl_add_u64 v[206:207], s[18:19], 0, v[0:1]
	s_mov_b32 m0, s51
	v_lshl_add_u64 v[210:211], s[24:25], 0, v[130:131]
	global_load_lds_dwordx4 v[206:207], off
	v_lshl_add_u64 v[206:207], s[18:19], 0, v[130:131]
	s_add_i32 m0, s51, 0x2000
	s_nop 0
	global_load_lds_dwordx4 v[206:207], off
	v_lshl_add_u64 v[206:207], s[24:25], 0, v[0:1]
	s_mov_b32 m0, s31
	s_nop 0
	global_load_lds_dwordx4 v[206:207], off
	s_mov_b32 m0, s36
	s_nop 0
	global_load_lds_dwordx4 v[210:211], off
	s_cmp_eq_u32 s50, -2
	s_cbranch_scc1 .Lp4b_f1
	s_waitcnt vmcnt(8)
	s_branch .Lp4b_j1

.Lp4b_j1:
	s_waitcnt lgkmcnt(0)
	s_barrier
	s_setprio 1
	s_waitcnt lgkmcnt(0)
	v_mfma_f32_16x16x32_bf16 v[62:65], v[136:139], v[170:173], v[62:65]
	v_mfma_f32_16x16x32_bf16 v[58:61], v[146:149], v[170:173], v[58:61]
	v_mfma_f32_16x16x32_bf16 v[50:53], v[136:139], v[178:181], v[50:53]
	v_mfma_f32_16x16x32_bf16 v[42:45], v[146:149], v[178:181], v[42:45]
	v_mfma_f32_16x16x32_bf16 v[34:37], v[136:139], v[186:189], v[34:37]
	v_mfma_f32_16x16x32_bf16 v[26:29], v[146:149], v[186:189], v[26:29]
	v_mfma_f32_16x16x32_bf16 v[18:21], v[136:139], v[194:197], v[18:21]
	v_mfma_f32_16x16x32_bf16 v[10:13], v[146:149], v[194:197], v[10:13]
	v_mfma_f32_16x16x32_bf16 v[62:65], v[140:143], v[174:177], v[62:65]
	v_mfma_f32_16x16x32_bf16 v[58:61], v[150:153], v[174:177], v[58:61]
	v_mfma_f32_16x16x32_bf16 v[50:53], v[140:143], v[182:185], v[50:53]
	v_mfma_f32_16x16x32_bf16 v[42:45], v[150:153], v[182:185], v[42:45]
	v_mfma_f32_16x16x32_bf16 v[34:37], v[140:143], v[190:193], v[34:37]
	v_mfma_f32_16x16x32_bf16 v[26:29], v[150:153], v[190:193], v[26:29]
	v_mfma_f32_16x16x32_bf16 v[18:21], v[140:143], v[198:201], v[18:21]
	v_mfma_f32_16x16x32_bf16 v[10:13], v[150:153], v[198:201], v[10:13]
	s_setprio 0
	s_setprio 1
	v_mfma_f32_16x16x32_bf16 v[54:57], v[154:157], v[170:173], v[54:57]
	v_mfma_f32_16x16x32_bf16 v[46:49], v[162:165], v[170:173], v[46:49]
	v_mfma_f32_16x16x32_bf16 v[38:41], v[154:157], v[178:181], v[38:41]
	v_mfma_f32_16x16x32_bf16 v[30:33], v[162:165], v[178:181], v[30:33]
	v_mfma_f32_16x16x32_bf16 v[22:25], v[154:157], v[186:189], v[22:25]
	v_mfma_f32_16x16x32_bf16 v[14:17], v[162:165], v[186:189], v[14:17]
	v_mfma_f32_16x16x32_bf16 v[6:9], v[154:157], v[194:197], v[6:9]
	v_mfma_f32_16x16x32_bf16 v[2:5], v[162:165], v[194:197], v[2:5]
	v_mfma_f32_16x16x32_bf16 v[54:57], v[158:161], v[174:177], v[54:57]
	v_mfma_f32_16x16x32_bf16 v[46:49], v[166:169], v[174:177], v[46:49]
	v_mfma_f32_16x16x32_bf16 v[38:41], v[158:161], v[182:185], v[38:41]
	v_mfma_f32_16x16x32_bf16 v[30:33], v[166:169], v[182:185], v[30:33]
	v_mfma_f32_16x16x32_bf16 v[22:25], v[158:161], v[190:193], v[22:25]
	v_mfma_f32_16x16x32_bf16 v[14:17], v[166:169], v[190:193], v[14:17]
	v_mfma_f32_16x16x32_bf16 v[6:9], v[158:161], v[198:201], v[6:9]
	v_mfma_f32_16x16x32_bf16 v[2:5], v[166:169], v[198:201], v[2:5]
	s_setprio 0
	s_barrier
	s_add_i32 s51, 0, 0x18000
	s_add_i32 s52, 0, 0x1c000
	v_add_u32_e32 v150, s51, v144
	v_add_u32_e32 v166, s52, v144
	ds_read_b128 v[136:139], v150
	ds_read_b128 v[140:143], v150 offset:1024
	ds_read_b128 v[146:149], v150 offset:2048
	ds_read_b128 v[150:153], v150 offset:3072
	ds_read_b128 v[154:157], v166
	ds_read_b128 v[158:161], v166 offset:1024
	ds_read_b128 v[162:165], v166 offset:2048
	ds_read_b128 v[166:169], v166 offset:3072
	s_add_u32 s18, s24, 0xb0000
	s_addc_u32 s19, s25, 0
	s_mov_b32 m0, s37
	v_lshl_add_u64 v[214:215], s[18:19], 0, v[0:1]
	ds_read_b128 v[170:173], v145 offset:32768
	ds_read_b128 v[174:177], v145 offset:33792
	ds_read_b128 v[178:181], v145 offset:34816
	ds_read_b128 v[182:185], v145 offset:35840
	ds_read_b128 v[186:189], v145 offset:36864
	ds_read_b128 v[190:193], v145 offset:37888
	ds_read_b128 v[194:197], v145 offset:38912
	ds_read_b128 v[198:201], v145 offset:39936
	global_load_lds_dwordx4 v[214:215], off
	v_lshl_add_u64 v[214:215], s[18:19], 0, v[130:131]
	s_mov_b32 m0, s38
	s_nop 0
	global_load_lds_dwordx4 v[214:215], off
	s_waitcnt vmcnt(8)
	s_waitcnt lgkmcnt(0)
	s_barrier
	s_setprio 1
	s_waitcnt lgkmcnt(0)
	v_mfma_f32_16x16x32_bf16 v[126:129], v[136:139], v[170:173], v[126:129]
	v_mfma_f32_16x16x32_bf16 v[122:125], v[146:149], v[170:173], v[122:125]
	v_mfma_f32_16x16x32_bf16 v[114:117], v[136:139], v[178:181], v[114:117]
	v_mfma_f32_16x16x32_bf16 v[106:109], v[146:149], v[178:181], v[106:109]
	v_mfma_f32_16x16x32_bf16 v[98:101], v[136:139], v[186:189], v[98:101]
	v_mfma_f32_16x16x32_bf16 v[90:93], v[146:149], v[186:189], v[90:93]
	v_mfma_f32_16x16x32_bf16 v[82:85], v[136:139], v[194:197], v[82:85]
	v_mfma_f32_16x16x32_bf16 v[74:77], v[146:149], v[194:197], v[74:77]
	v_mfma_f32_16x16x32_bf16 v[126:129], v[140:143], v[174:177], v[126:129]
	v_mfma_f32_16x16x32_bf16 v[122:125], v[150:153], v[174:177], v[122:125]
	v_mfma_f32_16x16x32_bf16 v[114:117], v[140:143], v[182:185], v[114:117]
	v_mfma_f32_16x16x32_bf16 v[106:109], v[150:153], v[182:185], v[106:109]
	v_mfma_f32_16x16x32_bf16 v[98:101], v[140:143], v[190:193], v[98:101]
	v_mfma_f32_16x16x32_bf16 v[90:93], v[150:153], v[190:193], v[90:93]
	v_mfma_f32_16x16x32_bf16 v[82:85], v[140:143], v[198:201], v[82:85]
	v_mfma_f32_16x16x32_bf16 v[74:77], v[150:153], v[198:201], v[74:77]
	s_setprio 0
	s_setprio 1
	v_mfma_f32_16x16x32_bf16 v[118:121], v[154:157], v[170:173], v[118:121]
	v_mfma_f32_16x16x32_bf16 v[110:113], v[162:165], v[170:173], v[110:113]
	v_mfma_f32_16x16x32_bf16 v[102:105], v[154:157], v[178:181], v[102:105]
	v_mfma_f32_16x16x32_bf16 v[94:97], v[162:165], v[178:181], v[94:97]
	v_mfma_f32_16x16x32_bf16 v[86:89], v[154:157], v[186:189], v[86:89]
	v_mfma_f32_16x16x32_bf16 v[78:81], v[162:165], v[186:189], v[78:81]
	v_mfma_f32_16x16x32_bf16 v[70:73], v[154:157], v[194:197], v[70:73]
	v_mfma_f32_16x16x32_bf16 v[66:69], v[162:165], v[194:197], v[66:69]
	v_mfma_f32_16x16x32_bf16 v[118:121], v[158:161], v[174:177], v[118:121]
	v_mfma_f32_16x16x32_bf16 v[110:113], v[166:169], v[174:177], v[110:113]
	v_mfma_f32_16x16x32_bf16 v[102:105], v[158:161], v[182:185], v[102:105]
	v_mfma_f32_16x16x32_bf16 v[94:97], v[166:169], v[182:185], v[94:97]
	v_mfma_f32_16x16x32_bf16 v[86:89], v[158:161], v[190:193], v[86:89]
	v_mfma_f32_16x16x32_bf16 v[78:81], v[166:169], v[190:193], v[78:81]
	v_mfma_f32_16x16x32_bf16 v[70:73], v[158:161], v[198:201], v[70:73]
	v_mfma_f32_16x16x32_bf16 v[66:69], v[166:169], v[198:201], v[66:69]
	s_setprio 0
	s_barrier
	s_add_i32 s18, s51, s30
	v_lshl_add_u64 v[202:203], v[202:203], 0, s[94:95]
	s_mov_b32 m0, s18
	ds_read_b128 v[170:173], v145 offset:49152
	ds_read_b128 v[174:177], v145 offset:50176
	ds_read_b128 v[178:181], v145 offset:51200
	ds_read_b128 v[182:185], v145 offset:52224
	ds_read_b128 v[186:189], v145 offset:53248
	ds_read_b128 v[190:193], v145 offset:54272
	ds_read_b128 v[194:197], v145 offset:55296
	ds_read_b128 v[198:201], v145 offset:56320
	global_load_lds_dwordx4 v[202:203], off
	s_add_i32 m0, s18, 0x2000
	s_add_u32 s18, s22, 0xb0080
	v_lshl_add_u64 v[202:203], v[204:205], 0, s[94:95]
	s_addc_u32 s19, s23, 0
	s_add_i32 s22, s52, s30
	global_load_lds_dwordx4 v[202:203], off
	v_lshl_add_u64 v[202:203], s[18:19], 0, v[0:1]
	s_mov_b32 m0, s22
	s_nop 0
	global_load_lds_dwordx4 v[202:203], off
	v_lshl_add_u64 v[202:203], s[18:19], 0, v[130:131]
	s_add_i32 m0, s22, 0x2000
	s_nop 0
	global_load_lds_dwordx4 v[202:203], off
	v_lshl_add_u64 v[202:203], v[206:207], 0, s[94:95]
	s_mov_b32 m0, s41
	s_nop 0
	global_load_lds_dwordx4 v[202:203], off
	v_lshl_add_u64 v[202:203], v[210:211], 0, s[94:95]
	s_mov_b32 m0, s42
	s_nop 0
	global_load_lds_dwordx4 v[202:203], off
	s_waitcnt vmcnt(8)
	s_waitcnt lgkmcnt(0)
	s_barrier
	s_setprio 1
	s_waitcnt lgkmcnt(0)
	v_mfma_f32_16x16x32_bf16 v[62:65], v[136:139], v[170:173], v[62:65]
	v_mfma_f32_16x16x32_bf16 v[58:61], v[146:149], v[170:173], v[58:61]
	v_mfma_f32_16x16x32_bf16 v[50:53], v[136:139], v[178:181], v[50:53]
	v_mfma_f32_16x16x32_bf16 v[42:45], v[146:149], v[178:181], v[42:45]
	v_mfma_f32_16x16x32_bf16 v[34:37], v[136:139], v[186:189], v[34:37]
	v_mfma_f32_16x16x32_bf16 v[26:29], v[146:149], v[186:189], v[26:29]
	v_mfma_f32_16x16x32_bf16 v[18:21], v[136:139], v[194:197], v[18:21]
	v_mfma_f32_16x16x32_bf16 v[10:13], v[146:149], v[194:197], v[10:13]
	v_mfma_f32_16x16x32_bf16 v[62:65], v[140:143], v[174:177], v[62:65]
	v_mfma_f32_16x16x32_bf16 v[58:61], v[150:153], v[174:177], v[58:61]
	v_mfma_f32_16x16x32_bf16 v[50:53], v[140:143], v[182:185], v[50:53]
	v_mfma_f32_16x16x32_bf16 v[42:45], v[150:153], v[182:185], v[42:45]
	v_mfma_f32_16x16x32_bf16 v[34:37], v[140:143], v[190:193], v[34:37]
	v_mfma_f32_16x16x32_bf16 v[26:29], v[150:153], v[190:193], v[26:29]
	v_mfma_f32_16x16x32_bf16 v[18:21], v[140:143], v[198:201], v[18:21]
	v_mfma_f32_16x16x32_bf16 v[10:13], v[150:153], v[198:201], v[10:13]
	s_setprio 0
	s_setprio 1
	v_mfma_f32_16x16x32_bf16 v[54:57], v[154:157], v[170:173], v[54:57]
	v_mfma_f32_16x16x32_bf16 v[46:49], v[162:165], v[170:173], v[46:49]
	v_mfma_f32_16x16x32_bf16 v[38:41], v[154:157], v[178:181], v[38:41]
	v_mfma_f32_16x16x32_bf16 v[30:33], v[162:165], v[178:181], v[30:33]
	v_mfma_f32_16x16x32_bf16 v[22:25], v[154:157], v[186:189], v[22:25]
	v_mfma_f32_16x16x32_bf16 v[14:17], v[162:165], v[186:189], v[14:17]
	v_mfma_f32_16x16x32_bf16 v[6:9], v[154:157], v[194:197], v[6:9]
	v_mfma_f32_16x16x32_bf16 v[2:5], v[162:165], v[194:197], v[2:5]
	v_mfma_f32_16x16x32_bf16 v[54:57], v[158:161], v[174:177], v[54:57]
	v_mfma_f32_16x16x32_bf16 v[46:49], v[166:169], v[174:177], v[46:49]
	v_mfma_f32_16x16x32_bf16 v[38:41], v[158:161], v[182:185], v[38:41]
	v_mfma_f32_16x16x32_bf16 v[30:33], v[166:169], v[182:185], v[30:33]
	v_mfma_f32_16x16x32_bf16 v[22:25], v[158:161], v[190:193], v[22:25]
	v_mfma_f32_16x16x32_bf16 v[14:17], v[166:169], v[190:193], v[14:17]
	v_mfma_f32_16x16x32_bf16 v[6:9], v[158:161], v[198:201], v[6:9]
	v_mfma_f32_16x16x32_bf16 v[2:5], v[166:169], v[198:201], v[2:5]
	s_setprio 0
	s_barrier
	s_add_i32 s50, s50, 2
	s_add_u32 s48, s48, 0x100
	s_addc_u32 s49, s49, 0
	s_cmp_gt_u32 s50, 41
	s_mov_b64 s[18:19], s[20:21]
	s_cbranch_scc0 .LBB0_1316
	s_and_b64 vcc, exec, s[14:15]
	s_cbranch_vccz .LBB0_1319
	s_barrier

.LBB0_1342:
	s_add_u32 s16, s14, 0x100
	s_addc_u32 s17, s15, 0
	s_add_i32 s47, 0, 0x10000
	s_cmp_eq_u32 s46, 40
	s_cselect_b32 s21, s9, s17
	s_cselect_b32 s20, s8, s16
	s_cselect_b32 s19, s13, s45
	s_cselect_b32 s18, s12, s44
	s_add_i32 s48, 0, 0x14000
	v_add_u32_e32 v148, s47, v166
	v_add_u32_e32 v164, s48, v166
	ds_read_b128 v[136:139], v148
	ds_read_b128 v[140:143], v148 offset:1024
	ds_read_b128 v[144:147], v148 offset:2048
	ds_read_b128 v[148:151], v148 offset:3072
	ds_read_b128 v[152:155], v164
	ds_read_b128 v[156:159], v164 offset:1024
	ds_read_b128 v[160:163], v164 offset:2048
	ds_read_b128 v[168:171], v164 offset:3072
	v_lshl_add_u64 v[164:165], s[14:15], 0, v[132:133]
	s_add_i32 m0, s23, 0xc000
	ds_read_b128 v[172:175], v167
	ds_read_b128 v[176:179], v167 offset:1024
	ds_read_b128 v[180:183], v167 offset:2048
	ds_read_b128 v[184:187], v167 offset:3072
	ds_read_b128 v[188:191], v167 offset:4096
	ds_read_b128 v[192:195], v167 offset:5120
	ds_read_b128 v[196:199], v167 offset:6144
	ds_read_b128 v[200:203], v167 offset:7168
	global_load_lds_dwordx4 v[164:165], off
	v_lshl_add_u64 v[164:165], s[14:15], 0, v[134:135]
	s_add_i32 m0, s23, 0xe000
	s_nop 0
	global_load_lds_dwordx4 v[164:165], off
	s_cmp_eq_u32 s46, -2
	s_cbranch_scc1 .Lp4a_f0
	s_waitcnt vmcnt(8)
	s_branch .Lp4a_j0

.Lp4a_j0:
	s_waitcnt lgkmcnt(0)
	s_barrier
	s_setprio 1
	s_waitcnt lgkmcnt(0)
	v_mfma_f32_16x16x32_bf16 v[126:129], v[136:139], v[172:175], v[126:129]
	v_mfma_f32_16x16x32_bf16 v[122:125], v[144:147], v[172:175], v[122:125]
	v_mfma_f32_16x16x32_bf16 v[114:117], v[136:139], v[180:183], v[114:117]
	v_mfma_f32_16x16x32_bf16 v[106:109], v[144:147], v[180:183], v[106:109]
	v_mfma_f32_16x16x32_bf16 v[98:101], v[136:139], v[188:191], v[98:101]
	v_mfma_f32_16x16x32_bf16 v[90:93], v[144:147], v[188:191], v[90:93]
	v_mfma_f32_16x16x32_bf16 v[82:85], v[136:139], v[196:199], v[82:85]
	v_mfma_f32_16x16x32_bf16 v[74:77], v[144:147], v[196:199], v[74:77]
	v_mfma_f32_16x16x32_bf16 v[126:129], v[140:143], v[176:179], v[126:129]
	v_mfma_f32_16x16x32_bf16 v[122:125], v[148:151], v[176:179], v[122:125]
	v_mfma_f32_16x16x32_bf16 v[114:117], v[140:143], v[184:187], v[114:117]
	v_mfma_f32_16x16x32_bf16 v[106:109], v[148:151], v[184:187], v[106:109]
	v_mfma_f32_16x16x32_bf16 v[98:101], v[140:143], v[192:195], v[98:101]
	v_mfma_f32_16x16x32_bf16 v[90:93], v[148:151], v[192:195], v[90:93]
	v_mfma_f32_16x16x32_bf16 v[82:85], v[140:143], v[200:203], v[82:85]
	v_mfma_f32_16x16x32_bf16 v[74:77], v[148:151], v[200:203], v[74:77]
	s_setprio 0
	s_setprio 1
	v_mfma_f32_16x16x32_bf16 v[118:121], v[152:155], v[172:175], v[118:121]
	v_mfma_f32_16x16x32_bf16 v[110:113], v[160:163], v[172:175], v[110:113]
	v_mfma_f32_16x16x32_bf16 v[102:105], v[152:155], v[180:183], v[102:105]
	v_mfma_f32_16x16x32_bf16 v[94:97], v[160:163], v[180:183], v[94:97]
	v_mfma_f32_16x16x32_bf16 v[86:89], v[152:155], v[188:191], v[86:89]
	v_mfma_f32_16x16x32_bf16 v[78:81], v[160:163], v[188:191], v[78:81]
	v_mfma_f32_16x16x32_bf16 v[70:73], v[152:155], v[196:199], v[70:73]
	v_mfma_f32_16x16x32_bf16 v[66:69], v[160:163], v[196:199], v[66:69]
	v_mfma_f32_16x16x32_bf16 v[118:121], v[156:159], v[176:179], v[118:121]
	v_mfma_f32_16x16x32_bf16 v[110:113], v[168:171], v[176:179], v[110:113]
	v_mfma_f32_16x16x32_bf16 v[102:105], v[156:159], v[184:187], v[102:105]
	v_mfma_f32_16x16x32_bf16 v[94:97], v[168:171], v[184:187], v[94:97]
	v_mfma_f32_16x16x32_bf16 v[86:89], v[156:159], v[192:195], v[86:89]
	v_mfma_f32_16x16x32_bf16 v[78:81], v[168:171], v[192:195], v[78:81]
	v_mfma_f32_16x16x32_bf16 v[70:73], v[156:159], v[200:203], v[70:73]
	v_mfma_f32_16x16x32_bf16 v[66:69], v[168:171], v[200:203], v[66:69]
	s_setprio 0
	s_barrier
	s_add_i32 s14, s47, s22
	v_lshl_add_u64 v[164:165], s[18:19], 0, v[0:1]
	s_mov_b32 m0, s14
	ds_read_b128 v[172:175], v167 offset:16384
	ds_read_b128 v[176:179], v167 offset:17408
	ds_read_b128 v[180:183], v167 offset:18432
	ds_read_b128 v[184:187], v167 offset:19456
	ds_read_b128 v[188:191], v167 offset:20480
	ds_read_b128 v[192:195], v167 offset:21504
	ds_read_b128 v[196:199], v167 offset:22528
	ds_read_b128 v[200:203], v167 offset:23552
	global_load_lds_dwordx4 v[164:165], off
	s_add_i32 m0, s14, 0x2000
	s_add_u32 s14, s18, 0xb0000
	v_lshl_add_u64 v[204:205], s[18:19], 0, v[130:131]
	s_addc_u32 s15, s19, 0
	s_add_i32 s47, s48, s22
	global_load_lds_dwordx4 v[204:205], off
	v_lshl_add_u64 v[206:207], s[14:15], 0, v[0:1]
	s_mov_b32 m0, s47
	v_lshl_add_u64 v[210:211], s[20:21], 0, v[130:131]
	global_load_lds_dwordx4 v[206:207], off
	v_lshl_add_u64 v[206:207], s[14:15], 0, v[130:131]
	s_add_i32 m0, s47, 0x2000
	s_nop 0
	global_load_lds_dwordx4 v[206:207], off
	v_lshl_add_u64 v[206:207], s[20:21], 0, v[0:1]
	s_mov_b32 m0, s23
	s_nop 0
	global_load_lds_dwordx4 v[206:207], off
	s_mov_b32 m0, s24
	s_nop 0
	global_load_lds_dwordx4 v[210:211], off
	s_cmp_eq_u32 s46, -2
	s_cbranch_scc1 .Lp4a_f1
	s_waitcnt vmcnt(8)
	s_branch .Lp4a_j1

.Lp4a_j1:
	s_waitcnt lgkmcnt(0)
	s_barrier
	s_setprio 1
	s_waitcnt lgkmcnt(0)
	v_mfma_f32_16x16x32_bf16 v[62:65], v[136:139], v[172:175], v[62:65]
	v_mfma_f32_16x16x32_bf16 v[58:61], v[144:147], v[172:175], v[58:61]
	v_mfma_f32_16x16x32_bf16 v[50:53], v[136:139], v[180:183], v[50:53]
	v_mfma_f32_16x16x32_bf16 v[42:45], v[144:147], v[180:183], v[42:45]
	v_mfma_f32_16x16x32_bf16 v[34:37], v[136:139], v[188:191], v[34:37]
	v_mfma_f32_16x16x32_bf16 v[26:29], v[144:147], v[188:191], v[26:29]
	v_mfma_f32_16x16x32_bf16 v[18:21], v[136:139], v[196:199], v[18:21]
	v_mfma_f32_16x16x32_bf16 v[10:13], v[144:147], v[196:199], v[10:13]
	v_mfma_f32_16x16x32_bf16 v[62:65], v[140:143], v[176:179], v[62:65]
	v_mfma_f32_16x16x32_bf16 v[58:61], v[148:151], v[176:179], v[58:61]
	v_mfma_f32_16x16x32_bf16 v[50:53], v[140:143], v[184:187], v[50:53]
	v_mfma_f32_16x16x32_bf16 v[42:45], v[148:151], v[184:187], v[42:45]
	v_mfma_f32_16x16x32_bf16 v[34:37], v[140:143], v[192:195], v[34:37]
	v_mfma_f32_16x16x32_bf16 v[26:29], v[148:151], v[192:195], v[26:29]
	v_mfma_f32_16x16x32_bf16 v[18:21], v[140:143], v[200:203], v[18:21]
	v_mfma_f32_16x16x32_bf16 v[10:13], v[148:151], v[200:203], v[10:13]
	s_setprio 0
	s_setprio 1
	v_mfma_f32_16x16x32_bf16 v[54:57], v[152:155], v[172:175], v[54:57]
	v_mfma_f32_16x16x32_bf16 v[46:49], v[160:163], v[172:175], v[46:49]
	v_mfma_f32_16x16x32_bf16 v[38:41], v[152:155], v[180:183], v[38:41]
	v_mfma_f32_16x16x32_bf16 v[30:33], v[160:163], v[180:183], v[30:33]
	v_mfma_f32_16x16x32_bf16 v[22:25], v[152:155], v[188:191], v[22:25]
	v_mfma_f32_16x16x32_bf16 v[14:17], v[160:163], v[188:191], v[14:17]
	v_mfma_f32_16x16x32_bf16 v[6:9], v[152:155], v[196:199], v[6:9]
	v_mfma_f32_16x16x32_bf16 v[2:5], v[160:163], v[196:199], v[2:5]
	v_mfma_f32_16x16x32_bf16 v[54:57], v[156:159], v[176:179], v[54:57]
	v_mfma_f32_16x16x32_bf16 v[46:49], v[168:171], v[176:179], v[46:49]
	v_mfma_f32_16x16x32_bf16 v[38:41], v[156:159], v[184:187], v[38:41]
	v_mfma_f32_16x16x32_bf16 v[30:33], v[168:171], v[184:187], v[30:33]
	v_mfma_f32_16x16x32_bf16 v[22:25], v[156:159], v[192:195], v[22:25]
	v_mfma_f32_16x16x32_bf16 v[14:17], v[168:171], v[192:195], v[14:17]
	v_mfma_f32_16x16x32_bf16 v[6:9], v[156:159], v[200:203], v[6:9]
	v_mfma_f32_16x16x32_bf16 v[2:5], v[168:171], v[200:203], v[2:5]
	s_setprio 0
	s_barrier
	s_add_i32 s47, 0, 0x18000
	s_add_i32 s48, 0, 0x1c000
	v_add_u32_e32 v148, s47, v166
	v_add_u32_e32 v168, s48, v166
	ds_read_b128 v[136:139], v148
	ds_read_b128 v[140:143], v148 offset:1024
	ds_read_b128 v[144:147], v148 offset:2048
	ds_read_b128 v[148:151], v148 offset:3072
	ds_read_b128 v[152:155], v168
	ds_read_b128 v[156:159], v168 offset:1024
	ds_read_b128 v[160:163], v168 offset:2048
	ds_read_b128 v[168:171], v168 offset:3072
	s_add_u32 s14, s20, 0xb0000
	s_addc_u32 s15, s21, 0
	s_mov_b32 m0, s25
	v_lshl_add_u64 v[214:215], s[14:15], 0, v[0:1]
	ds_read_b128 v[172:175], v167 offset:32768
	ds_read_b128 v[176:179], v167 offset:33792
	ds_read_b128 v[180:183], v167 offset:34816
	ds_read_b128 v[184:187], v167 offset:35840
	ds_read_b128 v[188:191], v167 offset:36864
	ds_read_b128 v[192:195], v167 offset:37888
	ds_read_b128 v[196:199], v167 offset:38912
	ds_read_b128 v[200:203], v167 offset:39936
	global_load_lds_dwordx4 v[214:215], off
	v_lshl_add_u64 v[214:215], s[14:15], 0, v[130:131]
	s_mov_b32 m0, s30
	s_nop 0
	global_load_lds_dwordx4 v[214:215], off
	s_waitcnt vmcnt(8)
	s_waitcnt lgkmcnt(0)
	s_barrier
	s_setprio 1
	s_waitcnt lgkmcnt(0)
	v_mfma_f32_16x16x32_bf16 v[126:129], v[136:139], v[172:175], v[126:129]
	v_mfma_f32_16x16x32_bf16 v[122:125], v[144:147], v[172:175], v[122:125]
	v_mfma_f32_16x16x32_bf16 v[114:117], v[136:139], v[180:183], v[114:117]
	v_mfma_f32_16x16x32_bf16 v[106:109], v[144:147], v[180:183], v[106:109]
	v_mfma_f32_16x16x32_bf16 v[98:101], v[136:139], v[188:191], v[98:101]
	v_mfma_f32_16x16x32_bf16 v[90:93], v[144:147], v[188:191], v[90:93]
	v_mfma_f32_16x16x32_bf16 v[82:85], v[136:139], v[196:199], v[82:85]
	v_mfma_f32_16x16x32_bf16 v[74:77], v[144:147], v[196:199], v[74:77]
	v_mfma_f32_16x16x32_bf16 v[126:129], v[140:143], v[176:179], v[126:129]
	v_mfma_f32_16x16x32_bf16 v[122:125], v[148:151], v[176:179], v[122:125]
	v_mfma_f32_16x16x32_bf16 v[114:117], v[140:143], v[184:187], v[114:117]
	v_mfma_f32_16x16x32_bf16 v[106:109], v[148:151], v[184:187], v[106:109]
	v_mfma_f32_16x16x32_bf16 v[98:101], v[140:143], v[192:195], v[98:101]
	v_mfma_f32_16x16x32_bf16 v[90:93], v[148:151], v[192:195], v[90:93]
	v_mfma_f32_16x16x32_bf16 v[82:85], v[140:143], v[200:203], v[82:85]
	v_mfma_f32_16x16x32_bf16 v[74:77], v[148:151], v[200:203], v[74:77]
	s_setprio 0
	s_setprio 1
	v_mfma_f32_16x16x32_bf16 v[118:121], v[152:155], v[172:175], v[118:121]
	v_mfma_f32_16x16x32_bf16 v[110:113], v[160:163], v[172:175], v[110:113]
	v_mfma_f32_16x16x32_bf16 v[102:105], v[152:155], v[180:183], v[102:105]
	v_mfma_f32_16x16x32_bf16 v[94:97], v[160:163], v[180:183], v[94:97]
	v_mfma_f32_16x16x32_bf16 v[86:89], v[152:155], v[188:191], v[86:89]
	v_mfma_f32_16x16x32_bf16 v[78:81], v[160:163], v[188:191], v[78:81]
	v_mfma_f32_16x16x32_bf16 v[70:73], v[152:155], v[196:199], v[70:73]
	v_mfma_f32_16x16x32_bf16 v[66:69], v[160:163], v[196:199], v[66:69]
	v_mfma_f32_16x16x32_bf16 v[118:121], v[156:159], v[176:179], v[118:121]
	v_mfma_f32_16x16x32_bf16 v[110:113], v[168:171], v[176:179], v[110:113]
	v_mfma_f32_16x16x32_bf16 v[102:105], v[156:159], v[184:187], v[102:105]
	v_mfma_f32_16x16x32_bf16 v[94:97], v[168:171], v[184:187], v[94:97]
	v_mfma_f32_16x16x32_bf16 v[86:89], v[156:159], v[192:195], v[86:89]
	v_mfma_f32_16x16x32_bf16 v[78:81], v[168:171], v[192:195], v[78:81]
	v_mfma_f32_16x16x32_bf16 v[70:73], v[156:159], v[200:203], v[70:73]
	v_mfma_f32_16x16x32_bf16 v[66:69], v[168:171], v[200:203], v[66:69]
	s_setprio 0
	s_barrier
	s_add_i32 s14, s47, s22
	v_lshl_add_u64 v[164:165], v[164:165], 0, s[94:95]
	s_mov_b32 m0, s14
	ds_read_b128 v[172:175], v167 offset:49152
	ds_read_b128 v[176:179], v167 offset:50176
	ds_read_b128 v[180:183], v167 offset:51200
	ds_read_b128 v[184:187], v167 offset:52224
	ds_read_b128 v[188:191], v167 offset:53248
	ds_read_b128 v[192:195], v167 offset:54272
	ds_read_b128 v[196:199], v167 offset:55296
	ds_read_b128 v[200:203], v167 offset:56320
	global_load_lds_dwordx4 v[164:165], off
	s_add_i32 m0, s14, 0x2000
	s_add_u32 s14, s18, 0xb0080
	v_lshl_add_u64 v[164:165], v[204:205], 0, s[94:95]
	s_addc_u32 s15, s19, 0
	s_add_i32 s18, s48, s22
	global_load_lds_dwordx4 v[164:165], off
	v_lshl_add_u64 v[164:165], s[14:15], 0, v[0:1]
	s_mov_b32 m0, s18
	s_nop 0
	global_load_lds_dwordx4 v[164:165], off
	v_lshl_add_u64 v[164:165], s[14:15], 0, v[130:131]
	s_add_i32 m0, s18, 0x2000
	s_nop 0
	global_load_lds_dwordx4 v[164:165], off
	v_lshl_add_u64 v[164:165], v[206:207], 0, s[94:95]
	s_mov_b32 m0, s37
	s_nop 0
	global_load_lds_dwordx4 v[164:165], off
	v_lshl_add_u64 v[164:165], v[210:211], 0, s[94:95]
	s_mov_b32 m0, s38
	s_nop 0
	global_load_lds_dwordx4 v[164:165], off
	s_waitcnt vmcnt(8)
	s_waitcnt lgkmcnt(0)
	s_barrier
	s_setprio 1
	s_waitcnt lgkmcnt(0)
	v_mfma_f32_16x16x32_bf16 v[62:65], v[136:139], v[172:175], v[62:65]
	v_mfma_f32_16x16x32_bf16 v[58:61], v[144:147], v[172:175], v[58:61]
	v_mfma_f32_16x16x32_bf16 v[50:53], v[136:139], v[180:183], v[50:53]
	v_mfma_f32_16x16x32_bf16 v[42:45], v[144:147], v[180:183], v[42:45]
	v_mfma_f32_16x16x32_bf16 v[34:37], v[136:139], v[188:191], v[34:37]
	v_mfma_f32_16x16x32_bf16 v[26:29], v[144:147], v[188:191], v[26:29]
	v_mfma_f32_16x16x32_bf16 v[18:21], v[136:139], v[196:199], v[18:21]
	v_mfma_f32_16x16x32_bf16 v[10:13], v[144:147], v[196:199], v[10:13]
	v_mfma_f32_16x16x32_bf16 v[62:65], v[140:143], v[176:179], v[62:65]
	v_mfma_f32_16x16x32_bf16 v[58:61], v[148:151], v[176:179], v[58:61]
	v_mfma_f32_16x16x32_bf16 v[50:53], v[140:143], v[184:187], v[50:53]
	v_mfma_f32_16x16x32_bf16 v[42:45], v[148:151], v[184:187], v[42:45]
	v_mfma_f32_16x16x32_bf16 v[34:37], v[140:143], v[192:195], v[34:37]
	v_mfma_f32_16x16x32_bf16 v[26:29], v[148:151], v[192:195], v[26:29]
	v_mfma_f32_16x16x32_bf16 v[18:21], v[140:143], v[200:203], v[18:21]
	v_mfma_f32_16x16x32_bf16 v[10:13], v[148:151], v[200:203], v[10:13]
	s_setprio 0
	s_setprio 1
	v_mfma_f32_16x16x32_bf16 v[54:57], v[152:155], v[172:175], v[54:57]
	v_mfma_f32_16x16x32_bf16 v[46:49], v[160:163], v[172:175], v[46:49]
	v_mfma_f32_16x16x32_bf16 v[38:41], v[152:155], v[180:183], v[38:41]
	v_mfma_f32_16x16x32_bf16 v[30:33], v[160:163], v[180:183], v[30:33]
	v_mfma_f32_16x16x32_bf16 v[22:25], v[152:155], v[188:191], v[22:25]
	v_mfma_f32_16x16x32_bf16 v[14:17], v[160:163], v[188:191], v[14:17]
	v_mfma_f32_16x16x32_bf16 v[6:9], v[152:155], v[196:199], v[6:9]
	v_mfma_f32_16x16x32_bf16 v[2:5], v[160:163], v[196:199], v[2:5]
	v_mfma_f32_16x16x32_bf16 v[54:57], v[156:159], v[176:179], v[54:57]
	v_mfma_f32_16x16x32_bf16 v[46:49], v[168:171], v[176:179], v[46:49]
	v_mfma_f32_16x16x32_bf16 v[38:41], v[156:159], v[184:187], v[38:41]
	v_mfma_f32_16x16x32_bf16 v[30:33], v[168:171], v[184:187], v[30:33]
	v_mfma_f32_16x16x32_bf16 v[22:25], v[156:159], v[192:195], v[22:25]
	v_mfma_f32_16x16x32_bf16 v[14:17], v[168:171], v[192:195], v[14:17]
	v_mfma_f32_16x16x32_bf16 v[6:9], v[156:159], v[200:203], v[6:9]
	v_mfma_f32_16x16x32_bf16 v[2:5], v[168:171], v[200:203], v[2:5]
	s_setprio 0
	s_barrier
	s_add_i32 s46, s46, 2
	s_add_u32 s44, s44, 0x100
	s_addc_u32 s45, s45, 0
	s_cmp_gt_u32 s46, 41
	s_mov_b64 s[14:15], s[16:17]
	s_cbranch_scc0 .LBB0_1342
	s_and_b64 vcc, exec, s[10:11]
	s_cbranch_vccz .LBB0_1345
	s_barrier
